# prompt attention: waves 4-7 start each tile loop ~600 cycles late via nop loop (stagger), plus barrier flatten
# baseline (speedup 1.0000x reference)
.LBB0_81:
	s_cmp_lt_i32 s31, s26
	s_cselect_b64 s[0:1], -1, 0
	s_cmp_gt_i32 s31, s22
	s_cselect_b64 s[12:13], -1, 0
	s_or_b64 s[0:1], s[0:1], s[12:13]
	s_and_b64 vcc, exec, s[0:1]
	s_cbranch_vccnz .LBB0_88
	s_lshl_b32 s0, s31, 6
	v_sub_u32_e32 v183, s0, v155
	s_mov_b32 s33, 0
	s_cmp_lt_u32 s62, 4
	s_cbranch_scc1 .Lpa0_nodelay
	s_movk_i32 s101, 20
.Lpa0_dly:
	s_nop 15
	s_sub_u32 s101, s101, 1
	s_cmp_lg_u32 s101, 0
	s_cbranch_scc1 .Lpa0_dly

.LBB0_90:
	s_or_b32 s0, s31, 1
	s_cmp_lt_i32 s0, s26
	s_cselect_b64 s[12:13], -1, 0
	s_cmp_ge_i32 s31, s22
	s_cselect_b64 s[14:15], -1, 0
	s_or_b64 s[12:13], s[14:15], s[12:13]
	s_and_b64 vcc, exec, s[12:13]
	s_cbranch_vccnz .LBB0_97
	s_lshl_b32 s0, s0, 6
	v_sub_u32_e32 v183, s0, v155
	s_mov_b32 s33, 0
	s_cmp_lt_u32 s62, 4
	s_cbranch_scc1 .Lpa1_nodelay
	s_movk_i32 s101, 20
